# v61 + K-loop heads placed at byte phase 32 mod 64 (.p2align 6 + 8 s_nop): placement variant
# baseline (speedup 1.0000x reference)
; template <class Epi, class Sched>
; __device__ __forceinline__ void gemm_phase(LAS unsigned char* lds, const Gemm g, const Sched& S, const Epi& E) {
;     ...
;     f32x4 acc[2][2][4][2];
; #pragma unroll
;     for (int a = 0; a < 2; ++a)
; #pragma unroll
;         for (int b = 0; b < 2; ++b)
; #pragma unroll
;             for (int m = 0; m < 4; ++m)
; #pragma unroll
;                 for (int n = 0; n < 2; ++n) acc[a][b][m][n] = (f32x4){0.f, 0.f, 0.f, 0.f};
;     ...
; #pragma unroll
;         for (int a = 0; a < 2; ++a)
; #pragma unroll
;             for (int b = 0; b < 2; ++b)
; #pragma unroll
;                 for (int m = 0; m < 4; ++m)
; #pragma unroll
;                     for (int n = 0; n < 2; ++n) acc[a][b][m][n] = (f32x4){0.f, 0.f, 0.f, 0.f};
.LBB0_129:
	s_andn2_b64 vcc, exec, s[40:41]
	v_mov_b64_e32 v[2:3], 0
	v_mov_b64_e32 v[4:5], 0
	v_mov_b64_e32 v[6:7], 0
	v_mov_b64_e32 v[8:9], 0
	v_mov_b64_e32 v[10:11], 0
	v_mov_b64_e32 v[12:13], 0
	v_mov_b64_e32 v[14:15], 0
	v_mov_b64_e32 v[16:17], 0
	v_mov_b64_e32 v[18:19], 0
	v_mov_b64_e32 v[20:21], 0
	v_mov_b64_e32 v[22:23], 0
	v_mov_b64_e32 v[24:25], 0
	v_mov_b64_e32 v[26:27], 0
	v_mov_b64_e32 v[28:29], 0
	v_mov_b64_e32 v[30:31], 0
	v_mov_b64_e32 v[32:33], 0
	v_mov_b64_e32 v[34:35], 0
	v_mov_b64_e32 v[36:37], 0
	v_mov_b64_e32 v[38:39], 0
	v_mov_b64_e32 v[40:41], 0
	v_mov_b64_e32 v[42:43], 0
	v_mov_b64_e32 v[44:45], 0
	v_mov_b64_e32 v[46:47], 0
	v_mov_b64_e32 v[48:49], 0
	v_mov_b64_e32 v[50:51], 0
	v_mov_b64_e32 v[52:53], 0
	v_mov_b64_e32 v[54:55], 0
	v_mov_b64_e32 v[56:57], 0
	v_mov_b64_e32 v[58:59], 0
	v_mov_b64_e32 v[60:61], 0
	v_mov_b64_e32 v[62:63], 0
	v_mov_b64_e32 v[64:65], 0
	v_mov_b64_e32 v[66:67], 0
	v_mov_b64_e32 v[68:69], 0
	v_mov_b64_e32 v[70:71], 0
	v_mov_b64_e32 v[72:73], 0
	v_mov_b64_e32 v[74:75], 0
	v_mov_b64_e32 v[76:77], 0
	v_mov_b64_e32 v[78:79], 0
	v_mov_b64_e32 v[80:81], 0
	v_mov_b64_e32 v[82:83], 0
	v_mov_b64_e32 v[84:85], 0
	v_mov_b64_e32 v[86:87], 0
	v_mov_b64_e32 v[88:89], 0
	v_mov_b64_e32 v[90:91], 0
	v_mov_b64_e32 v[92:93], 0
	v_mov_b64_e32 v[94:95], 0
	v_mov_b64_e32 v[96:97], 0
	v_mov_b64_e32 v[98:99], 0
	v_mov_b64_e32 v[100:101], 0
	v_mov_b64_e32 v[102:103], 0
	v_mov_b64_e32 v[104:105], 0
	v_mov_b64_e32 v[106:107], 0
	v_mov_b64_e32 v[108:109], 0
	v_mov_b64_e32 v[110:111], 0
	v_mov_b64_e32 v[112:113], 0
	v_mov_b64_e32 v[114:115], 0
	v_mov_b64_e32 v[116:117], 0
	v_mov_b64_e32 v[118:119], 0
	v_mov_b64_e32 v[120:121], 0
	v_mov_b64_e32 v[122:123], 0
	v_mov_b64_e32 v[124:125], 0
	v_mov_b64_e32 v[126:127], 0
	v_mov_b64_e32 v[128:129], 0
	s_cbranch_vccnz .LBB0_132
	s_add_u32 s9, s46, 0x100
	s_addc_u32 s36, s47, 0
	s_mov_b32 s50, 0
	s_mov_b64 s[46:47], 0
	.p2align	6
	s_nop 0
	s_nop 0
	s_nop 0
	s_nop 0
	s_nop 0
	s_nop 0
	s_nop 0
	s_nop 0

; template <class Epi, class Sched>
; __device__ __forceinline__ void gemm_phase(LAS unsigned char* lds, const Gemm g, const Sched& S, const Epi& E) {
;     ...
;     f32x4 acc[2][2][4][2];
; #pragma unroll
;     for (int a = 0; a < 2; ++a)
; #pragma unroll
;         for (int b = 0; b < 2; ++b)
; #pragma unroll
;             for (int m = 0; m < 4; ++m)
; #pragma unroll
;                 for (int n = 0; n < 2; ++n) acc[a][b][m][n] = (f32x4){0.f, 0.f, 0.f, 0.f};
;     ...
; #pragma unroll
;         for (int a = 0; a < 2; ++a)
; #pragma unroll
;             for (int b = 0; b < 2; ++b)
; #pragma unroll
;                 for (int m = 0; m < 4; ++m)
; #pragma unroll
;                     for (int n = 0; n < 2; ++n) acc[a][b][m][n] = (f32x4){0.f, 0.f, 0.f, 0.f};
.LBB0_416:
	s_andn2_b64 vcc, exec, s[42:43]
	v_mov_b64_e32 v[2:3], 0
	v_mov_b64_e32 v[4:5], 0
	v_mov_b64_e32 v[6:7], 0
	v_mov_b64_e32 v[8:9], 0
	v_mov_b64_e32 v[10:11], 0
	v_mov_b64_e32 v[12:13], 0
	v_mov_b64_e32 v[14:15], 0
	v_mov_b64_e32 v[16:17], 0
	v_mov_b64_e32 v[18:19], 0
	v_mov_b64_e32 v[20:21], 0
	v_mov_b64_e32 v[22:23], 0
	v_mov_b64_e32 v[24:25], 0
	v_mov_b64_e32 v[26:27], 0
	v_mov_b64_e32 v[28:29], 0
	v_mov_b64_e32 v[30:31], 0
	v_mov_b64_e32 v[32:33], 0
	v_mov_b64_e32 v[34:35], 0
	v_mov_b64_e32 v[36:37], 0
	v_mov_b64_e32 v[38:39], 0
	v_mov_b64_e32 v[40:41], 0
	v_mov_b64_e32 v[42:43], 0
	v_mov_b64_e32 v[44:45], 0
	v_mov_b64_e32 v[46:47], 0
	v_mov_b64_e32 v[48:49], 0
	v_mov_b64_e32 v[50:51], 0
	v_mov_b64_e32 v[52:53], 0
	v_mov_b64_e32 v[54:55], 0
	v_mov_b64_e32 v[56:57], 0
	v_mov_b64_e32 v[58:59], 0
	v_mov_b64_e32 v[60:61], 0
	v_mov_b64_e32 v[62:63], 0
	v_mov_b64_e32 v[64:65], 0
	v_mov_b64_e32 v[66:67], 0
	v_mov_b64_e32 v[68:69], 0
	v_mov_b64_e32 v[70:71], 0
	v_mov_b64_e32 v[72:73], 0
	v_mov_b64_e32 v[74:75], 0
	v_mov_b64_e32 v[76:77], 0
	v_mov_b64_e32 v[78:79], 0
	v_mov_b64_e32 v[80:81], 0
	v_mov_b64_e32 v[82:83], 0
	v_mov_b64_e32 v[84:85], 0
	v_mov_b64_e32 v[86:87], 0
	v_mov_b64_e32 v[88:89], 0
	v_mov_b64_e32 v[90:91], 0
	v_mov_b64_e32 v[92:93], 0
	v_mov_b64_e32 v[94:95], 0
	v_mov_b64_e32 v[96:97], 0
	v_mov_b64_e32 v[98:99], 0
	v_mov_b64_e32 v[100:101], 0
	v_mov_b64_e32 v[102:103], 0
	v_mov_b64_e32 v[104:105], 0
	v_mov_b64_e32 v[106:107], 0
	v_mov_b64_e32 v[108:109], 0
	v_mov_b64_e32 v[110:111], 0
	v_mov_b64_e32 v[112:113], 0
	v_mov_b64_e32 v[114:115], 0
	v_mov_b64_e32 v[116:117], 0
	v_mov_b64_e32 v[118:119], 0
	v_mov_b64_e32 v[120:121], 0
	v_mov_b64_e32 v[122:123], 0
	v_mov_b64_e32 v[124:125], 0
	v_mov_b64_e32 v[126:127], 0
	v_mov_b64_e32 v[128:129], 0
	s_cbranch_vccnz .LBB0_419
	s_add_u32 s9, s48, 0x100
	s_addc_u32 s36, s49, 0
	s_mov_b32 s52, 0
	s_mov_b64 s[48:49], 0
	.p2align	6
	s_nop 0
	s_nop 0
	s_nop 0
	s_nop 0
	s_nop 0
	s_nop 0
	s_nop 0
	s_nop 0
